# P9 epilogue: nt on the last-use residual X1 loads only, on top of P6 residual nt
# speedup vs baseline: 1.0009x; 1.0009x over previous
.LBB0_1022:
	s_ashr_i32 s23, s30, 5
	v_lshl_or_b32 v0, s55, 8, v182
	s_mul_hi_i32 s25, s23, 0x18000
	s_mul_i32 s23, s23, 0x18000
	s_add_u32 s36, s48, s23
	v_ashrrev_i32_e32 v1, 31, v0
	s_addc_u32 s37, s49, s25
	v_lshlrev_b64 v[0:1], 2, v[0:1]
	v_lshl_add_u64 v[10:11], s[36:37], 0, v[0:1]
	global_load_dwordx4 v[2:5], v[10:11], off nt
	global_load_dwordx4 v[6:9], v[10:11], off offset:64 nt
	global_load_dwordx4 v[22:25], v[10:11], off offset:512 nt
	global_load_dwordx4 v[26:29], v[10:11], off offset:576 nt
	v_lshl_add_u32 v10, s30, 8, v180
	v_ashrrev_i32_e32 v11, 31, v10
	v_lshl_add_u64 v[18:19], s[4:5], 0, v[0:1]
	v_lshlrev_b64 v[20:21], 14, v[10:11]
	v_lshl_add_u64 v[12:13], v[18:19], 0, v[20:21]
	global_load_dwordx4 v[172:175], v[12:13], off nt
	global_load_dwordx4 v[176:179], v[12:13], off offset:64 nt
	global_load_dwordx4 v[188:191], v[12:13], off offset:512 nt
	global_load_dwordx4 v[192:195], v[12:13], off offset:576 nt
	v_or_b32_e32 v12, 16, v10
	v_ashrrev_i32_e32 v13, 31, v12
	v_lshlrev_b64 v[12:13], 14, v[12:13]
	v_lshl_add_u64 v[14:15], v[18:19], 0, v[12:13]
	global_load_dwordx4 v[196:199], v[14:15], off nt
	global_load_dwordx4 v[200:203], v[14:15], off offset:64 nt
	global_load_dwordx4 v[204:207], v[14:15], off offset:512 nt
	global_load_dwordx4 v[208:211], v[14:15], off offset:576 nt
	v_or_b32_e32 v14, 32, v10
	v_ashrrev_i32_e32 v15, 31, v14
	v_lshlrev_b64 v[14:15], 14, v[14:15]
	v_lshl_add_u64 v[16:17], v[18:19], 0, v[14:15]
	global_load_dwordx4 v[212:215], v[16:17], off nt
	global_load_dwordx4 v[216:219], v[16:17], off offset:64 nt
	global_load_dwordx4 v[220:223], v[16:17], off offset:512 nt
	v_or_b32_e32 v10, 48, v10
	global_load_dwordx4 v[224:227], v[16:17], off offset:576 nt
	v_ashrrev_i32_e32 v11, 31, v10
	v_lshlrev_b64 v[244:245], 14, v[10:11]
	v_lshl_add_u64 v[10:11], v[18:19], 0, v[244:245]
	global_load_dwordx4 v[228:231], v[10:11], off nt
	global_load_dwordx4 v[232:235], v[10:11], off offset:64 nt
	global_load_dwordx4 v[236:239], v[10:11], off offset:512 nt
	global_load_dwordx4 v[240:243], v[10:11], off offset:576 nt
	v_lshl_add_u64 v[10:11], s[4:5], 0, v[20:21]
	v_lshl_add_u64 v[246:247], v[10:11], 0, v[0:1]
	v_lshl_add_u64 v[10:11], s[4:5], 0, v[12:13]
	v_lshl_add_u64 v[12:13], s[4:5], 0, v[14:15]
	v_lshl_add_u64 v[248:249], v[10:11], 0, v[0:1]
	v_lshl_add_u64 v[250:251], v[12:13], 0, v[0:1]
	s_andn2_b64 vcc, exec, s[0:1]
	s_mov_b64 s[0:1], -1
	s_waitcnt vmcnt(0)
	v_pk_mul_f32 v[14:15], v[4:5], s[14:15] op_sel_hi:[1,0]
	v_pk_mul_f32 v[16:17], v[2:3], s[14:15] op_sel_hi:[1,0]
	v_pk_mul_f32 v[10:11], v[8:9], s[14:15] op_sel_hi:[1,0]
	v_pk_mul_f32 v[12:13], v[6:7], s[14:15] op_sel_hi:[1,0]
	v_pk_mul_f32 v[6:7], v[24:25], s[14:15] op_sel_hi:[1,0]
	v_pk_mul_f32 v[8:9], v[22:23], s[14:15] op_sel_hi:[1,0]
	v_pk_mul_f32 v[2:3], v[28:29], s[14:15] op_sel_hi:[1,0]
	v_pk_mul_f32 v[4:5], v[26:27], s[14:15] op_sel_hi:[1,0]
	v_pk_fma_f32 v[24:25], v[158:159], v[14:15], v[174:175]
	v_pk_fma_f32 v[22:23], v[156:157], v[16:17], v[172:173]
	v_pk_fma_f32 v[28:29], v[154:155], v[10:11], v[178:179]
	v_pk_fma_f32 v[26:27], v[152:153], v[12:13], v[176:177]
	v_pk_fma_f32 v[138:139], v[138:139], v[6:7], v[190:191]
	v_pk_fma_f32 v[136:137], v[136:137], v[8:9], v[188:189]
	v_pk_fma_f32 v[134:135], v[134:135], v[2:3], v[194:195]
	v_pk_fma_f32 v[132:133], v[132:133], v[4:5], v[192:193]
	v_pk_fma_f32 v[150:151], v[150:151], v[14:15], v[198:199]
	v_pk_fma_f32 v[148:149], v[148:149], v[16:17], v[196:197]
	v_pk_fma_f32 v[146:147], v[146:147], v[10:11], v[202:203]
	v_pk_fma_f32 v[144:145], v[144:145], v[12:13], v[200:201]
	v_pk_fma_f32 v[130:131], v[130:131], v[6:7], v[206:207]
	v_pk_fma_f32 v[128:129], v[128:129], v[8:9], v[204:205]
	v_pk_fma_f32 v[122:123], v[122:123], v[2:3], v[210:211]
	v_pk_fma_f32 v[120:121], v[120:121], v[4:5], v[208:209]
	v_pk_fma_f32 v[142:143], v[142:143], v[14:15], v[214:215]
	v_pk_fma_f32 v[140:141], v[140:141], v[16:17], v[212:213]
	global_store_dwordx4 v[246:247], v[22:25], off
	global_store_dwordx4 v[246:247], v[26:29], off offset:64
	global_store_dwordx4 v[246:247], v[136:139], off offset:512
	global_store_dwordx4 v[246:247], v[132:135], off offset:576
	global_store_dwordx4 v[248:249], v[148:151], off
	global_store_dwordx4 v[248:249], v[144:147], off offset:64
	global_store_dwordx4 v[248:249], v[128:131], off offset:512
	global_store_dwordx4 v[248:249], v[120:123], off offset:576
	global_store_dwordx4 v[250:251], v[140:143], off
	v_pk_fma_f32 v[24:25], v[114:115], v[6:7], v[222:223]
	v_pk_fma_f32 v[22:23], v[112:113], v[8:9], v[220:221]
	global_store_dwordx4 v[250:251], v[22:25], off offset:512
	v_lshl_add_u64 v[26:27], s[4:5], 0, v[244:245]
	v_lshl_add_u64 v[26:27], v[26:27], 0, v[0:1]
	v_pk_fma_f32 v[24:25], v[106:107], v[2:3], v[226:227]
	v_pk_fma_f32 v[22:23], v[104:105], v[4:5], v[224:225]
	global_store_dwordx4 v[250:251], v[22:25], off offset:576
	v_pk_fma_f32 v[30:31], v[126:127], v[10:11], v[218:219]
	v_pk_fma_f32 v[28:29], v[124:125], v[12:13], v[216:217]
	v_pk_fma_f32 v[24:25], v[118:119], v[14:15], v[230:231]
	v_pk_fma_f32 v[22:23], v[116:117], v[16:17], v[228:229]
	global_store_dwordx4 v[26:27], v[22:25], off
	global_store_dwordx4 v[250:251], v[28:31], off offset:64
	v_lshl_add_u64 v[148:149], v[20:21], 0, s[16:17]
	v_pk_fma_f32 v[24:25], v[110:111], v[10:11], v[234:235]
	v_pk_fma_f32 v[22:23], v[108:109], v[12:13], v[232:233]
	global_store_dwordx4 v[26:27], v[22:25], off offset:64
	v_lshl_add_u64 v[30:31], v[20:21], 0, s[8:9]
	v_lshl_add_u64 v[104:105], v[18:19], 0, v[30:31]
	v_pk_fma_f32 v[24:25], v[102:103], v[6:7], v[238:239]
	v_pk_fma_f32 v[22:23], v[100:101], v[8:9], v[236:237]
	global_store_dwordx4 v[26:27], v[22:25], off offset:512
	v_lshl_add_u64 v[116:117], v[18:19], 0, v[148:149]
	v_lshl_add_u64 v[150:151], v[20:21], 0, s[18:19]
	v_pk_fma_f32 v[24:25], v[98:99], v[2:3], v[242:243]
	v_pk_fma_f32 v[22:23], v[96:97], v[4:5], v[240:241]
	global_store_dwordx4 v[26:27], v[22:25], off offset:576
	v_lshl_add_u64 v[152:153], v[20:21], 0, s[20:21]
	global_load_dwordx4 v[22:25], v[104:105], off nt
	global_load_dwordx4 v[26:29], v[104:105], off offset:64 nt
	global_load_dwordx4 v[96:99], v[104:105], off offset:512 nt
	global_load_dwordx4 v[100:103], v[104:105], off offset:576 nt
	s_nop 0
	global_load_dwordx4 v[104:107], v[116:117], off nt
	global_load_dwordx4 v[108:111], v[116:117], off offset:64 nt
	global_load_dwordx4 v[112:115], v[116:117], off offset:512 nt
	s_nop 0
	global_load_dwordx4 v[116:119], v[116:117], off offset:576 nt
	v_lshl_add_u64 v[132:133], v[18:19], 0, v[150:151]
	v_lshl_add_u64 v[144:145], v[18:19], 0, v[152:153]
	global_load_dwordx4 v[120:123], v[132:133], off nt
	global_load_dwordx4 v[124:127], v[132:133], off offset:64 nt
	global_load_dwordx4 v[128:131], v[132:133], off offset:512 nt
	s_nop 0
	global_load_dwordx4 v[132:135], v[132:133], off offset:576 nt
	s_nop 0
	global_load_dwordx4 v[18:21], v[144:145], off nt
	global_load_dwordx4 v[136:139], v[144:145], off offset:64 nt
	global_load_dwordx4 v[140:143], v[144:145], off offset:512 nt
	s_nop 0
	global_load_dwordx4 v[144:147], v[144:145], off offset:576 nt
	v_lshl_add_u64 v[30:31], s[4:5], 0, v[30:31]
	v_lshl_add_u64 v[148:149], s[4:5], 0, v[148:149]
	v_lshl_add_u64 v[150:151], s[4:5], 0, v[150:151]
	v_lshl_add_u64 v[30:31], v[30:31], 0, v[0:1]
	v_lshl_add_u64 v[148:149], v[148:149], 0, v[0:1]
	v_lshl_add_u64 v[150:151], v[150:151], 0, v[0:1]
	s_waitcnt vmcnt(15)
	v_pk_fma_f32 v[24:25], v[94:95], v[14:15], v[24:25]
	v_pk_fma_f32 v[22:23], v[92:93], v[16:17], v[22:23]
	s_waitcnt vmcnt(14)
	v_pk_fma_f32 v[28:29], v[90:91], v[10:11], v[28:29]
	v_pk_fma_f32 v[26:27], v[88:89], v[12:13], v[26:27]
	s_waitcnt vmcnt(13)
	v_pk_fma_f32 v[74:75], v[74:75], v[6:7], v[98:99]
	v_pk_fma_f32 v[72:73], v[72:73], v[8:9], v[96:97]
	s_waitcnt vmcnt(12)
	v_pk_fma_f32 v[70:71], v[70:71], v[2:3], v[102:103]
	v_pk_fma_f32 v[68:69], v[68:69], v[4:5], v[100:101]
	s_waitcnt vmcnt(11)
	v_pk_fma_f32 v[86:87], v[86:87], v[14:15], v[106:107]
	v_pk_fma_f32 v[84:85], v[84:85], v[16:17], v[104:105]
	s_waitcnt vmcnt(10)
	v_pk_fma_f32 v[82:83], v[82:83], v[10:11], v[110:111]
	v_pk_fma_f32 v[80:81], v[80:81], v[12:13], v[108:109]
	s_waitcnt vmcnt(9)
	v_pk_fma_f32 v[62:63], v[62:63], v[6:7], v[114:115]
	v_pk_fma_f32 v[60:61], v[60:61], v[8:9], v[112:113]
	s_waitcnt vmcnt(8)
	v_pk_fma_f32 v[58:59], v[58:59], v[2:3], v[118:119]
	v_pk_fma_f32 v[56:57], v[56:57], v[4:5], v[116:117]
	s_waitcnt vmcnt(7)
	v_pk_fma_f32 v[78:79], v[78:79], v[14:15], v[122:123]
	v_pk_fma_f32 v[76:77], v[76:77], v[16:17], v[120:121]
	s_waitcnt vmcnt(6)
	v_pk_fma_f32 v[66:67], v[66:67], v[10:11], v[126:127]
	v_pk_fma_f32 v[64:65], v[64:65], v[12:13], v[124:125]
	global_store_dwordx4 v[30:31], v[22:25], off
	global_store_dwordx4 v[30:31], v[26:29], off offset:64
	global_store_dwordx4 v[30:31], v[72:75], off offset:512
	global_store_dwordx4 v[30:31], v[68:71], off offset:576
	global_store_dwordx4 v[148:149], v[84:87], off
	global_store_dwordx4 v[148:149], v[80:83], off offset:64
	global_store_dwordx4 v[148:149], v[60:63], off offset:512
	global_store_dwordx4 v[148:149], v[56:59], off offset:576
	global_store_dwordx4 v[150:151], v[76:79], off
	global_store_dwordx4 v[150:151], v[64:67], off offset:64
	s_waitcnt vmcnt(15)
	v_pk_fma_f32 v[24:25], v[50:51], v[6:7], v[130:131]
	v_pk_fma_f32 v[22:23], v[48:49], v[8:9], v[128:129]
	s_waitcnt vmcnt(13)
	v_pk_fma_f32 v[20:21], v[54:55], v[14:15], v[20:21]
	v_lshl_add_u64 v[14:15], s[4:5], 0, v[152:153]
	global_store_dwordx4 v[150:151], v[22:25], off offset:512
	v_pk_fma_f32 v[18:19], v[52:53], v[16:17], v[18:19]
	v_lshl_add_u64 v[16:17], v[14:15], 0, v[0:1]
	v_pk_fma_f32 v[24:25], v[42:43], v[2:3], v[134:135]
	v_pk_fma_f32 v[22:23], v[40:41], v[4:5], v[132:133]
	s_waitcnt vmcnt(13)
	v_pk_fma_f32 v[14:15], v[46:47], v[10:11], v[138:139]
	v_pk_fma_f32 v[12:13], v[44:45], v[12:13], v[136:137]
	s_waitcnt vmcnt(12)
	v_pk_fma_f32 v[10:11], v[38:39], v[6:7], v[142:143]
	v_pk_fma_f32 v[8:9], v[36:37], v[8:9], v[140:141]
	s_waitcnt vmcnt(11)
	v_pk_fma_f32 v[2:3], v[34:35], v[2:3], v[146:147]
	v_pk_fma_f32 v[0:1], v[32:33], v[4:5], v[144:145]
	global_store_dwordx4 v[150:151], v[22:25], off offset:576
	global_store_dwordx4 v[16:17], v[18:21], off
	global_store_dwordx4 v[16:17], v[12:15], off offset:64
	global_store_dwordx4 v[16:17], v[8:11], off offset:512
	global_store_dwordx4 v[16:17], v[0:3], off offset:576
	s_cbranch_vccnz .LBB0_1011
	s_nop 7
	s_andn2_b64 vcc, exec, s[10:11]
	s_cbranch_vccnz .LBB0_1010
	s_barrier
	s_branch .LBB0_1010
